# skew odd CUs by ~24us at start of in-proj chain to de-collide epilogue store bursts
# speedup vs baseline: 1.0017x; 1.0017x over previous
; #define EP_LAS __attribute__((address_space(3)))
;     __device__ void init(int M, int N, int G_, int c_) { S0.init(M, N, 1, 0); c = c_; G = G_; }
; #define WTS(off) (WSP(bf16raw, WS_WTS) + (off))
; __global__ void __launch_bounds__(512, 2) mega_fwd(Args a) {
;     ...
;     for (int ph = ph_lo; ph < ph_hi; ++ph) {
;         unsigned char* ws = (unsigned char*)rd_ptr(ldsl, 25); float* xout = (float*)rd_ptr(ldsl, 24);
;         const int L = ph / NSUB, sidx = ph % NSUB, k = sidx < 2 ? sidx : sidx == 2 ? 14 : sidx == 3 ? 15 : sidx - 2;
;         int G = gridDim.x, bx = blockIdx.x; asm volatile("" : "+s"(G), "+s"(bx));
;         bool need_sync = true;
;     ...
;         } else if (k == 1) {
;             need_sync = false;
;             if (PHON(1)) {
;             pg8::Gemm g{WSP(bf16raw, WS_XB2), WTS(W_IN), TT, 3072, DM}; pg8::StaticOrder S; S.init(TT, 3072, G, bx);
;             pg8::Unit u0_; S.next(0, u0_); const ep::RstdCache rc_ = ep::rstd_prep<32>(WSP(float, WS_SSA), u0_.pm, 1.0f / 2048.0f, 1e-6f, (EP_LAS float*)(ldsl + 131072)); ep::EpiQKV E{rc_, WSP(float, WS_SSA), WSP(bf16raw, WS_ZQKV), WSP(float, WS_COSP), WSP(float, WS_SINP)};
;             pg8::gemm_phase<ep::EpiQKV, pg8::StaticOrder, GP_ALIGN, GP_SP2>(ldsl, g, S, E); }
.LBB0_18:
	s_load_dword s30, s[96:97], 0x0
	s_mov_b32 s2, s94
	s_cmp_lg_u32 s82, 1
	s_cbranch_scc1 .Lskew_done
	s_bitcmp1_b32 s2, 3
	s_cbranch_scc0 .Lskew_done
	s_mov_b32 s98, 8
.Lskew_loop:
	s_sleep 94
	s_add_i32 s98, s98, -1
	s_cmp_lg_u32 s98, 0
	s_cbranch_scc1 .Lskew_loop
.Lskew_done:
	s_cmp_lg_u32 s54, 32
	s_waitcnt lgkmcnt(0)
	s_mov_b32 s73, s30
	s_cbranch_scc0 .LBB0_42
	s_ashr_i32 s58, s0, 4
	v_writelane_b32 v254, s30, 58
	s_mov_b64 s[0:1], -1
	s_mov_b64 s[20:21], 0
	s_cmp_lt_i32 s82, 7
	s_mov_b64 s[48:49], 0
	s_mov_b64 s[46:47], 0
	s_cbranch_scc1 .LBB0_536
	s_cmp_gt_i32 s82, 10
	s_cbranch_scc0 .LBB0_43
	s_cmp_gt_i32 s82, 13
	s_cbranch_scc0 .LBB0_224
	s_cmp_gt_i32 s82, 14
	s_cbranch_scc0 .LBB0_274
	s_mov_b64 s[46:47], -1
	s_mov_b64 s[22:23], 0
	s_cmp_eq_u32 s82, 15
	s_cbranch_scc0 .LBB0_275
	s_cmpk_lt_i32 s2, 0x100
	s_cselect_b64 s[10:11], -1, 0
	s_cmpk_gt_i32 s2, 0xff
	s_mov_b32 s4, s72
	s_cbranch_scc1 .LBB0_30
	s_ashr_i32 s0, s2, 31
	s_lshr_b32 s0, s0, 29
	s_add_i32 s4, s2, s0
	s_and_b32 s0, s4, -8
	s_sub_i32 s5, s2, s0
	s_cmp_gt_i32 s5, -1
	s_mov_b64 s[0:1], -1
	s_cbranch_scc0 .LBB0_27
	s_lshl_b32 s8, s5, 5
	s_mov_b64 s[0:1], 0
